# stack2: + redundant GLA chunk-staging barrier removed (gate inputs are read by the wave that wrote them), RWKV step-loop nops dropped
# baseline (speedup 1.0000x reference)
.Lrwkv_step2:
	s_waitcnt lgkmcnt(10)
	v_pk_mul_f32 v[216:217], v[130:131], v[0:1] op_sel:[0,0] op_sel_hi:[1,0]
	v_pk_fma_f32 v[216:217], v[132:133], v[0:1], v[216:217] op_sel:[0,1,0] op_sel_hi:[1,1,1]
	v_pk_fma_f32 v[130:131], v[146:147], v[56:57], v[130:131] op_sel:[0,0,0] op_sel_hi:[1,0,1]
	v_pk_fma_f32 v[216:217], v[134:135], v[2:3], v[216:217] op_sel:[0,0,0] op_sel_hi:[1,0,1]
	v_pk_fma_f32 v[132:133], v[146:147], v[56:57], v[132:133] op_sel:[0,1,0] op_sel_hi:[1,1,1]
	v_pk_fma_f32 v[216:217], v[136:137], v[2:3], v[216:217] op_sel:[0,1,0] op_sel_hi:[1,1,1]
	v_pk_fma_f32 v[134:135], v[146:147], v[58:59], v[134:135] op_sel:[0,0,0] op_sel_hi:[1,0,1]
	v_pk_fma_f32 v[216:217], v[138:139], v[4:5], v[216:217] op_sel:[0,0,0] op_sel_hi:[1,0,1]
	v_pk_fma_f32 v[136:137], v[146:147], v[58:59], v[136:137] op_sel:[0,1,0] op_sel_hi:[1,1,1]
	v_pk_fma_f32 v[216:217], v[140:141], v[4:5], v[216:217] op_sel:[0,1,0] op_sel_hi:[1,1,1]
	v_pk_fma_f32 v[138:139], v[146:147], v[60:61], v[138:139] op_sel:[0,0,0] op_sel_hi:[1,0,1]
	v_pk_fma_f32 v[216:217], v[142:143], v[6:7], v[216:217] op_sel:[0,0,0] op_sel_hi:[1,0,1]
	v_pk_fma_f32 v[140:141], v[146:147], v[60:61], v[140:141] op_sel:[0,1,0] op_sel_hi:[1,1,1]
	v_pk_fma_f32 v[216:217], v[144:145], v[6:7], v[216:217] op_sel:[0,1,0] op_sel_hi:[1,1,1]
	v_pk_fma_f32 v[142:143], v[146:147], v[62:63], v[142:143] op_sel:[0,0,0] op_sel_hi:[1,0,1]
	v_pk_fma_f32 v[144:145], v[146:147], v[62:63], v[144:145] op_sel:[0,1,0] op_sel_hi:[1,1,1]
	v_add_f32_dpp v216, v216, v216 quad_perm:[1,0,3,2] row_mask:0xf bank_mask:0xf bound_ctrl:1
	v_add_f32_dpp v217, v217, v217 quad_perm:[1,0,3,2] row_mask:0xf bank_mask:0xf bound_ctrl:1
	ds_read_b128 v[0:3], v112 offset:16896
	v_add_f32_dpp v216, v216, v216 quad_perm:[2,3,0,1] row_mask:0xf bank_mask:0xf bound_ctrl:1
	v_add_f32_dpp v217, v217, v217 quad_perm:[2,3,0,1] row_mask:0xf bank_mask:0xf bound_ctrl:1
	ds_read_b128 v[4:7], v112 offset:16912
	v_add_f32_dpp v216, v216, v216 row_half_mirror row_mask:0xf bank_mask:0xf bound_ctrl:1
	v_add_f32_dpp v217, v217, v217 row_half_mirror row_mask:0xf bank_mask:0xf bound_ctrl:1
	v_pk_fma_f32 v[130:131], v[216:217], v[48:49], v[130:131] op_sel:[0,0,0] op_sel_hi:[1,0,1]
	v_pk_fma_f32 v[132:133], v[216:217], v[48:49], v[132:133] op_sel:[0,1,0] op_sel_hi:[1,1,1]
	v_pk_mul_f32 v[238:239], v[130:131], v[64:65] op_sel:[0,0] op_sel_hi:[1,0]
	v_pk_fma_f32 v[134:135], v[216:217], v[50:51], v[134:135] op_sel:[0,0,0] op_sel_hi:[1,0,1]
	v_pk_fma_f32 v[238:239], v[132:133], v[64:65], v[238:239] op_sel:[0,1,0] op_sel_hi:[1,1,1]
	v_pk_fma_f32 v[136:137], v[216:217], v[50:51], v[136:137] op_sel:[0,1,0] op_sel_hi:[1,1,1]
	v_pk_fma_f32 v[238:239], v[134:135], v[66:67], v[238:239] op_sel:[0,0,0] op_sel_hi:[1,0,1]
	v_pk_fma_f32 v[138:139], v[216:217], v[52:53], v[138:139] op_sel:[0,0,0] op_sel_hi:[1,0,1]
	v_pk_fma_f32 v[238:239], v[136:137], v[66:67], v[238:239] op_sel:[0,1,0] op_sel_hi:[1,1,1]
	v_pk_fma_f32 v[140:141], v[216:217], v[52:53], v[140:141] op_sel:[0,1,0] op_sel_hi:[1,1,1]
	v_pk_fma_f32 v[238:239], v[138:139], v[68:69], v[238:239] op_sel:[0,0,0] op_sel_hi:[1,0,1]
	v_pk_fma_f32 v[142:143], v[216:217], v[54:55], v[142:143] op_sel:[0,0,0] op_sel_hi:[1,0,1]
	v_pk_fma_f32 v[238:239], v[140:141], v[68:69], v[238:239] op_sel:[0,1,0] op_sel_hi:[1,1,1]
	v_pk_fma_f32 v[144:145], v[216:217], v[54:55], v[144:145] op_sel:[0,1,0] op_sel_hi:[1,1,1]
	v_pk_fma_f32 v[238:239], v[142:143], v[70:71], v[238:239] op_sel:[0,0,0] op_sel_hi:[1,0,1]
	ds_read_b128 v[48:51], v112 offset:25088
	v_pk_fma_f32 v[238:239], v[144:145], v[70:71], v[238:239] op_sel:[0,1,0] op_sel_hi:[1,1,1]
	ds_read_b128 v[52:55], v112 offset:25104
	ds_read_b128 v[56:59], v112 offset:8704
	v_add_f32_dpp v238, v238, v238 quad_perm:[1,0,3,2] row_mask:0xf bank_mask:0xf bound_ctrl:1
	v_add_f32_dpp v239, v239, v239 quad_perm:[1,0,3,2] row_mask:0xf bank_mask:0xf bound_ctrl:1
	ds_read_b128 v[60:63], v112 offset:8720
	v_add_f32_dpp v238, v238, v238 quad_perm:[2,3,0,1] row_mask:0xf bank_mask:0xf bound_ctrl:1
	v_add_f32_dpp v239, v239, v239 quad_perm:[2,3,0,1] row_mask:0xf bank_mask:0xf bound_ctrl:1
	ds_read_b128 v[64:67], v112 offset:33280
	v_add_f32_dpp v238, v238, v238 row_half_mirror row_mask:0xf bank_mask:0xf bound_ctrl:1
	v_add_f32_dpp v239, v239, v239 row_half_mirror row_mask:0xf bank_mask:0xf bound_ctrl:1
	ds_read_b128 v[68:71], v112 offset:33296
	ds_read_b64 v[146:147], v214 offset:41472
	s_and_saveexec_b64 s[36:37], s[8:9]
	ds_write_b64 v214, v[238:239] offset:49152
	s_or_b64 exec, exec, s[36:37]
	s_waitcnt lgkmcnt(10)
	v_pk_mul_f32 v[216:217], v[130:131], v[72:73] op_sel:[0,0] op_sel_hi:[1,0]
	v_pk_fma_f32 v[216:217], v[132:133], v[72:73], v[216:217] op_sel:[0,1,0] op_sel_hi:[1,1,1]
	v_pk_fma_f32 v[130:131], v[148:149], v[96:97], v[130:131] op_sel:[0,0,0] op_sel_hi:[1,0,1]
	v_pk_fma_f32 v[216:217], v[134:135], v[74:75], v[216:217] op_sel:[0,0,0] op_sel_hi:[1,0,1]
	v_pk_fma_f32 v[132:133], v[148:149], v[96:97], v[132:133] op_sel:[0,1,0] op_sel_hi:[1,1,1]
	v_pk_fma_f32 v[216:217], v[136:137], v[74:75], v[216:217] op_sel:[0,1,0] op_sel_hi:[1,1,1]
	v_pk_fma_f32 v[134:135], v[148:149], v[98:99], v[134:135] op_sel:[0,0,0] op_sel_hi:[1,0,1]
	v_pk_fma_f32 v[216:217], v[138:139], v[76:77], v[216:217] op_sel:[0,0,0] op_sel_hi:[1,0,1]
	v_pk_fma_f32 v[136:137], v[148:149], v[98:99], v[136:137] op_sel:[0,1,0] op_sel_hi:[1,1,1]
	v_pk_fma_f32 v[216:217], v[140:141], v[76:77], v[216:217] op_sel:[0,1,0] op_sel_hi:[1,1,1]
	v_pk_fma_f32 v[138:139], v[148:149], v[100:101], v[138:139] op_sel:[0,0,0] op_sel_hi:[1,0,1]
	v_pk_fma_f32 v[216:217], v[142:143], v[78:79], v[216:217] op_sel:[0,0,0] op_sel_hi:[1,0,1]
	v_pk_fma_f32 v[140:141], v[148:149], v[100:101], v[140:141] op_sel:[0,1,0] op_sel_hi:[1,1,1]
	v_pk_fma_f32 v[216:217], v[144:145], v[78:79], v[216:217] op_sel:[0,1,0] op_sel_hi:[1,1,1]
	v_pk_fma_f32 v[142:143], v[148:149], v[102:103], v[142:143] op_sel:[0,0,0] op_sel_hi:[1,0,1]
	v_pk_fma_f32 v[144:145], v[148:149], v[102:103], v[144:145] op_sel:[0,1,0] op_sel_hi:[1,1,1]
	v_add_f32_dpp v216, v216, v216 quad_perm:[1,0,3,2] row_mask:0xf bank_mask:0xf bound_ctrl:1
	v_add_f32_dpp v217, v217, v217 quad_perm:[1,0,3,2] row_mask:0xf bank_mask:0xf bound_ctrl:1
	ds_read_b128 v[72:75], v112 offset:17152
	v_add_f32_dpp v216, v216, v216 quad_perm:[2,3,0,1] row_mask:0xf bank_mask:0xf bound_ctrl:1
	v_add_f32_dpp v217, v217, v217 quad_perm:[2,3,0,1] row_mask:0xf bank_mask:0xf bound_ctrl:1
	ds_read_b128 v[76:79], v112 offset:17168
	v_add_f32_dpp v216, v216, v216 row_half_mirror row_mask:0xf bank_mask:0xf bound_ctrl:1
	v_add_f32_dpp v217, v217, v217 row_half_mirror row_mask:0xf bank_mask:0xf bound_ctrl:1
	v_pk_fma_f32 v[130:131], v[216:217], v[88:89], v[130:131] op_sel:[0,0,0] op_sel_hi:[1,0,1]
	v_pk_fma_f32 v[132:133], v[216:217], v[88:89], v[132:133] op_sel:[0,1,0] op_sel_hi:[1,1,1]
	v_pk_mul_f32 v[238:239], v[130:131], v[104:105] op_sel:[0,0] op_sel_hi:[1,0]
	v_pk_fma_f32 v[134:135], v[216:217], v[90:91], v[134:135] op_sel:[0,0,0] op_sel_hi:[1,0,1]
	v_pk_fma_f32 v[238:239], v[132:133], v[104:105], v[238:239] op_sel:[0,1,0] op_sel_hi:[1,1,1]
	v_pk_fma_f32 v[136:137], v[216:217], v[90:91], v[136:137] op_sel:[0,1,0] op_sel_hi:[1,1,1]
	v_pk_fma_f32 v[238:239], v[134:135], v[106:107], v[238:239] op_sel:[0,0,0] op_sel_hi:[1,0,1]
	v_pk_fma_f32 v[138:139], v[216:217], v[92:93], v[138:139] op_sel:[0,0,0] op_sel_hi:[1,0,1]
	v_pk_fma_f32 v[238:239], v[136:137], v[106:107], v[238:239] op_sel:[0,1,0] op_sel_hi:[1,1,1]
	v_pk_fma_f32 v[140:141], v[216:217], v[92:93], v[140:141] op_sel:[0,1,0] op_sel_hi:[1,1,1]
	v_pk_fma_f32 v[238:239], v[138:139], v[108:109], v[238:239] op_sel:[0,0,0] op_sel_hi:[1,0,1]
	v_pk_fma_f32 v[142:143], v[216:217], v[94:95], v[142:143] op_sel:[0,0,0] op_sel_hi:[1,0,1]
	v_pk_fma_f32 v[238:239], v[140:141], v[108:109], v[238:239] op_sel:[0,1,0] op_sel_hi:[1,1,1]
	v_pk_fma_f32 v[144:145], v[216:217], v[94:95], v[144:145] op_sel:[0,1,0] op_sel_hi:[1,1,1]
	v_pk_fma_f32 v[238:239], v[142:143], v[110:111], v[238:239] op_sel:[0,0,0] op_sel_hi:[1,0,1]
	ds_read_b128 v[88:91], v112 offset:25344
	v_pk_fma_f32 v[238:239], v[144:145], v[110:111], v[238:239] op_sel:[0,1,0] op_sel_hi:[1,1,1]
	ds_read_b128 v[92:95], v112 offset:25360
	ds_read_b128 v[96:99], v112 offset:8960
	v_add_f32_dpp v238, v238, v238 quad_perm:[1,0,3,2] row_mask:0xf bank_mask:0xf bound_ctrl:1
	v_add_f32_dpp v239, v239, v239 quad_perm:[1,0,3,2] row_mask:0xf bank_mask:0xf bound_ctrl:1
	ds_read_b128 v[100:103], v112 offset:8976
	v_add_f32_dpp v238, v238, v238 quad_perm:[2,3,0,1] row_mask:0xf bank_mask:0xf bound_ctrl:1
	v_add_f32_dpp v239, v239, v239 quad_perm:[2,3,0,1] row_mask:0xf bank_mask:0xf bound_ctrl:1
	ds_read_b128 v[104:107], v112 offset:33536
	v_add_f32_dpp v238, v238, v238 row_half_mirror row_mask:0xf bank_mask:0xf bound_ctrl:1
	v_add_f32_dpp v239, v239, v239 row_half_mirror row_mask:0xf bank_mask:0xf bound_ctrl:1
	ds_read_b128 v[108:111], v112 offset:33552
	ds_read_b64 v[148:149], v214 offset:41728
	s_and_saveexec_b64 s[36:37], s[8:9]
	ds_write_b64 v214, v[238:239] offset:49408
	s_or_b64 exec, exec, s[36:37]
	s_add_i32 s48, s48, 2
	v_add_u32_e32 v112, 0x200, v112
	v_add_u32_e32 v214, 0x200, v214
	s_cmp_lt_u32 s48, 32
	s_cbranch_scc1 .Lrwkv_step2
	ds_read_b128 v[8:11], v158 offset:7936
	ds_read_b128 v[12:15], v158 offset:7952
	s_waitcnt lgkmcnt(0)
	v_pk_mul_f32 v[130:131], v[130:131], v[8:9] op_sel:[0,0] op_sel_hi:[1,0]
	v_pk_mul_f32 v[132:133], v[132:133], v[8:9] op_sel:[0,1] op_sel_hi:[1,1]
	v_pk_mul_f32 v[134:135], v[134:135], v[10:11] op_sel:[0,0] op_sel_hi:[1,0]
	v_pk_mul_f32 v[136:137], v[136:137], v[10:11] op_sel:[0,1] op_sel_hi:[1,1]
	v_pk_mul_f32 v[138:139], v[138:139], v[12:13] op_sel:[0,0] op_sel_hi:[1,0]
	v_pk_mul_f32 v[140:141], v[140:141], v[12:13] op_sel:[0,1] op_sel_hi:[1,1]
	v_pk_mul_f32 v[142:143], v[142:143], v[14:15] op_sel:[0,0] op_sel_hi:[1,0]
	v_pk_mul_f32 v[144:145], v[144:145], v[14:15] op_sel:[0,1] op_sel_hi:[1,1]
	s_branch .LBB0_1599

.LBB0_3089:
	s_waitcnt vmcnt(2)
	v_and_b32_e32 v76, 0xffff, v32
	v_lshrrev_b32_e32 v77, 16, v32
	s_waitcnt vmcnt(1)
	v_lshl_or_b32 v76, v36, 16, v76
	v_and_or_b32 v77, v36, s84, v77
	v_add_u32_e32 v78, 0xd000, v189
	ds_write_b128 v185, v[0:3]
	ds_write_b128 v185, v[4:7] offset:17408
	ds_write_b128 v186, v[8:11]
	ds_write_b128 v186, v[12:15] offset:17408
	ds_write_b128 v187, v[16:19]
	ds_write_b128 v187, v[20:23] offset:17408
	ds_write_b128 v188, v[24:27]
	ds_write_b128 v188, v[28:31] offset:17408
	ds_write2_b32 v78, v76, v77 offset1:36
	v_and_b32_e32 v76, 0xffff, v33
	v_lshrrev_b32_e32 v77, 16, v33
	v_lshl_or_b32 v76, v37, 16, v76
	v_and_or_b32 v77, v37, s84, v77
	ds_write2_b32 v78, v76, v77 offset0:72 offset1:108
	v_and_b32_e32 v76, 0xffff, v34
	v_lshrrev_b32_e32 v77, 16, v34
	v_lshl_or_b32 v76, v38, 16, v76
	v_and_or_b32 v77, v38, s84, v77
	ds_write2_b32 v78, v76, v77 offset0:144 offset1:180
	v_and_b32_e32 v76, 0xffff, v35
	v_lshrrev_b32_e32 v77, 16, v35
	v_lshl_or_b32 v76, v39, 16, v76
	v_and_or_b32 v77, v39, s84, v77
	s_cmp_eq_u32 s93, 35
	ds_write2_b32 v78, v76, v77 offset0:216 offset1:252
	s_waitcnt vmcnt(0)
	ds_write_b128 v190, v[40:43] offset:62464
	s_waitcnt lgkmcnt(0)
	s_cbranch_scc1 .LBB0_3091
	s_cmp_lt_u32 s93, 3
	s_cselect_b32 s48, 0xff, s85
	s_add_i32 s94, s48, s75
	s_and_b64 s[48:49], s[72:73], exec
	s_cselect_b32 s48, s92, s94
	v_add_u32_e32 v2, s48, v211
	v_ashrrev_i32_e32 v3, 31, v2
	v_lshl_add_u64 v[8:9], v[2:3], 0, s[70:71]
	v_add_u32_e32 v2, s48, v212
	v_ashrrev_i32_e32 v3, 31, v2
	v_add_u32_e32 v0, s48, v210
	v_lshl_add_u64 v[16:17], v[2:3], 0, s[70:71]
	v_add_u32_e32 v2, s48, v213
	v_add_u32_e32 v32, s48, v113
	v_add_u32_e32 v34, s48, v214
	v_add_u32_e32 v40, s48, v215
	v_ashrrev_i32_e32 v1, 31, v0
	v_ashrrev_i32_e32 v3, 31, v2
	v_ashrrev_i32_e32 v33, 31, v32
	v_ashrrev_i32_e32 v35, 31, v34
	v_ashrrev_i32_e32 v41, 31, v40
	v_lshl_add_u64 v[0:1], v[0:1], 0, s[70:71]
	v_lshl_add_u64 v[24:25], v[2:3], 0, s[70:71]
	v_lshl_add_u64 v[32:33], v[32:33], 0, s[70:71]
	v_lshl_add_u64 v[34:35], v[34:35], 0, s[70:71]
	v_lshl_add_u64 v[40:41], v[40:41], 0, s[70:71]
	v_lshlrev_b64 v[0:1], 10, v[0:1]
	v_lshlrev_b64 v[8:9], 10, v[8:9]
	v_lshlrev_b64 v[16:17], 10, v[16:17]
	v_lshlrev_b64 v[24:25], 10, v[24:25]
	v_lshlrev_b64 v[32:33], 11, v[32:33]
	v_lshlrev_b64 v[34:35], 11, v[34:35]
	v_lshlrev_b64 v[40:41], 7, v[40:41]
	v_lshl_add_u64 v[2:3], v[136:137], 0, v[0:1]
	v_lshl_add_u64 v[4:5], v[138:139], 0, v[0:1]
	v_lshl_add_u64 v[10:11], v[136:137], 0, v[8:9]
	v_lshl_add_u64 v[12:13], v[138:139], 0, v[8:9]
	v_lshl_add_u64 v[18:19], v[136:137], 0, v[16:17]
	v_lshl_add_u64 v[20:21], v[138:139], 0, v[16:17]
	v_lshl_add_u64 v[26:27], v[136:137], 0, v[24:25]
	v_lshl_add_u64 v[28:29], v[138:139], 0, v[24:25]
	v_lshl_add_u64 v[32:33], v[140:141], 0, v[32:33]
	v_lshl_add_u64 v[36:37], v[140:141], 0, v[34:35]
	v_lshl_add_u64 v[40:41], v[142:143], 0, v[40:41]
	global_load_dwordx4 v[0:3], v[2:3], off
	s_nop 0
	global_load_dwordx4 v[4:7], v[4:5], off
	s_nop 0
	global_load_dwordx4 v[8:11], v[10:11], off
	s_nop 0
	global_load_dwordx4 v[12:15], v[12:13], off
	s_nop 0
	global_load_dwordx4 v[16:19], v[18:19], off
	s_nop 0
	global_load_dwordx4 v[20:23], v[20:21], off
	s_nop 0
	global_load_dwordx4 v[24:27], v[26:27], off
	s_nop 0
	global_load_dwordx4 v[28:31], v[28:29], off
	s_nop 0
	global_load_dwordx4 v[32:35], v[32:33], off
	s_nop 0
	global_load_dwordx4 v[36:39], v[36:37], off
	s_nop 0
	global_load_dwordx4 v[40:43], v[40:41], off
